# P1 norm: batch-aligned row mapping so norm gain/shift/scale stay in registers for 7 of 9 rows per wave (x-only loop body)
# speedup vs baseline: 1.0133x; 1.0072x over previous
.LBB0_81:
	v_readlane_b32 s4, v252, 0
	v_writelane_b32 v250, s2, 19
	s_and_b64 s[0:1], s[2:3], exec
	v_readlane_b32 s5, v252, 1
	v_readlane_b32 s6, v252, 2
	v_readlane_b32 s7, v252, 3
	v_readlane_b32 s8, v252, 4
	v_readlane_b32 s9, v252, 5
	v_readlane_b32 s10, v252, 6
	v_readlane_b32 s11, v252, 7
	v_writelane_b32 v250, s3, 20
	s_mov_b64 s[22:23], s[10:11]
	v_readlane_b32 s0, v252, 35
	v_readlane_b32 s1, v252, 36
	s_cselect_b32 s1, s1, s23
	s_cselect_b32 s0, s0, s22
	v_writelane_b32 v250, s0, 21
	v_readlane_b32 s5, v252, 40
	v_readlane_b32 s4, v252, 39
	v_writelane_b32 v250, s1, 22
	v_readlane_b32 s0, v252, 29
	s_cselect_b32 s49, s5, s0
	v_readlane_b32 s0, v252, 28
	v_mov_b32_e32 v2, v1
	s_cselect_b32 s48, s4, s0
	v_readlane_b32 s0, v252, 30
	v_ashrrev_i32_e32 v3, 6, v2
	v_readlane_b32 s12, v252, 47
	v_add_u32_e32 v34, s0, v3
	v_and_b32_e32 v35, 0xff, v34
	v_lshrrev_b32_e32 v34, 8, v34
	v_lshl_or_b32 v34, v34, 11, v35
	s_movk_i32 s0, 0x4800
	v_readlane_b32 s2, v252, 37
	v_readlane_b32 s13, v252, 48
	s_movk_i32 s12, 0x47ff
	v_cmp_gt_i32_e32 vcc, s0, v34
	v_readlane_b32 s3, v252, 38
	v_readlane_b32 s6, v252, 41
	v_readlane_b32 s7, v252, 42
	v_readlane_b32 s8, v252, 43
	v_readlane_b32 s9, v252, 44
	v_readlane_b32 s10, v252, 45
	v_readlane_b32 s11, v252, 46
	v_readlane_b32 s14, v252, 49
	v_readlane_b32 s15, v252, 50
	s_and_saveexec_b64 s[0:1], vcc
	v_readlane_b32 s2, v252, 62
	v_readlane_b32 s13, v251, 18
	s_cbranch_execz .LBB0_86
	v_readlane_b32 s4, v250, 2
	v_readlane_b32 s5, v250, 3
	s_mul_i32 s42, s4, 0xd800
	s_mov_b32 s8, s4
	s_lshl_b64 s[4:5], s[42:43], 2
	v_readlane_b32 s3, v252, 31
	s_add_u32 s6, s3, s4
	v_readlane_b32 s3, v252, 32
	s_addc_u32 s7, s3, s5
	s_lshl_b32 s42, s8, 11
	v_readlane_b32 s52, v252, 35
	s_lshl_b64 s[4:5], s[42:43], 2
	v_readlane_b32 s60, v252, 43
	v_lshlrev_b32_e32 v2, 2, v2
	v_readlane_b32 s61, v252, 44
	s_add_u32 s4, s60, s4
	v_and_b32_e32 v2, 0xfc, v2
	s_addc_u32 s5, s61, s5
	v_lshlrev_b32_e32 v194, 2, v2
	v_cmp_lt_i32_e32 vcc, v235, v234
	v_or_b32_e32 v10, 0x400, v2
	v_lshl_add_u64 v[36:37], s[4:5], 0, v[194:195]
	v_cndmask_b32_e32 v3, v233, v235, vcc
	v_cmp_lt_i32_e32 vcc, v236, v234
	v_lshlrev_b32_e32 v194, 2, v10
	v_or_b32_e32 v12, 0x500, v2
	v_lshlrev_b32_e32 v67, 2, v3
	v_cndmask_b32_e32 v3, v233, v236, vcc
	v_cmp_lt_i32_e32 vcc, v237, v234
	v_lshl_add_u64 v[38:39], s[4:5], 0, v[194:195]
	v_lshlrev_b32_e32 v194, 2, v12
	v_or_b32_e32 v14, 0x600, v2
	v_lshlrev_b32_e32 v76, 2, v3
	v_cndmask_b32_e32 v3, v233, v237, vcc
	v_cmp_lt_i32_e32 vcc, v238, v234
	v_lshl_add_u64 v[40:41], s[4:5], 0, v[194:195]
	v_lshlrev_b32_e32 v194, 2, v14
	v_or_b32_e32 v16, 0x700, v2
	v_lshlrev_b32_e32 v77, 2, v3
	v_cndmask_b32_e32 v3, v233, v238, vcc
	v_cmp_lt_i32_e32 vcc, v239, v234
	v_lshl_add_u64 v[42:43], s[4:5], 0, v[194:195]
	v_lshlrev_b32_e32 v194, 2, v16
	v_readlane_b32 s64, v252, 47
	v_readlane_b32 s65, v252, 48
	v_readlane_b32 s8, v250, 10
	v_lshlrev_b32_e32 v78, 2, v3
	v_cndmask_b32_e32 v3, v233, v239, vcc
	v_cmp_lt_i32_e32 vcc, v240, v234
	v_lshl_add_u64 v[44:45], s[4:5], 0, v[194:195]
	v_ashrrev_i32_e32 v35, 31, v34
	v_readlane_b32 s4, v250, 21
	v_readlane_b32 s66, v252, 49
	v_readlane_b32 s64, v250, 8
	v_readlane_b32 s14, v251, 52
	v_readlane_b32 s9, v250, 11
	v_lshlrev_b32_e32 v79, 2, v3
	v_cndmask_b32_e32 v3, v233, v240, vcc
	v_or_b32_e32 v4, 0x100, v2
	v_or_b32_e32 v6, 0x200, v2
	v_or_b32_e32 v8, 0x300, v2
	v_lshlrev_b32_e32 v194, 1, v2
	v_lshlrev_b64 v[18:19], 13, v[34:35]
	v_readlane_b32 s5, v250, 22
	v_readlane_b32 s66, v250, 17
	v_readlane_b32 s65, v250, 9
	s_mov_b64 s[22:23], 0x2000
	s_mov_b32 s34, 0x5040100
	v_readlane_b32 s15, v251, 53
	s_mov_b32 s21, s9
	v_lshlrev_b32_e32 v80, 2, v3
	v_lshl_add_u64 v[46:47], s[96:97], 0, v[194:195]
	v_lshl_add_u64 v[48:49], s[4:5], 0, v[18:19]
	s_mov_b64 s[8:9], 0
	v_lshlrev_b32_e32 v50, 2, v2
	v_mov_b32_e32 v51, v195
	v_lshlrev_b32_e32 v52, 2, v4
	v_mov_b32_e32 v53, v195
	v_lshlrev_b32_e32 v54, 2, v6
	v_mov_b32_e32 v55, v195
	v_lshlrev_b32_e32 v56, 2, v8
	v_mov_b32_e32 v57, v195
	v_lshlrev_b32_e32 v58, 2, v10
	v_mov_b32_e32 v59, v195
	v_lshlrev_b32_e32 v60, 2, v12
	v_mov_b32_e32 v61, v195
	v_lshlrev_b32_e32 v62, 2, v14
	v_mov_b32_e32 v63, v195
	v_lshlrev_b32_e32 v64, 2, v16
	v_mov_b32_e32 v65, v195
	v_readlane_b32 s53, v252, 36
	v_readlane_b32 s54, v252, 37
	v_readlane_b32 s55, v252, 38
	v_readlane_b32 s56, v252, 39
	v_readlane_b32 s57, v252, 40
	v_readlane_b32 s58, v252, 41
	v_readlane_b32 s59, v252, 42
	v_readlane_b32 s62, v252, 45
	v_readlane_b32 s63, v252, 46
	v_readlane_b32 s67, v252, 50
	s_branch .LBB0_84
.LBB0_83:
	s_or_b64 exec, exec, s[10:11]
	v_lshl_add_u64 v[2:3], v[2:3], 0, v[50:51]
	v_readfirstlane_b32 s32, v34
	s_mov_b64 s[98:99], 0x200000
	s_nop 1
	s_and_b32 s35, s32, 0x700
	s_cmp_eq_u32 s35, 0
	s_cbranch_scc1 .Lnorm_full
	s_cmp_ge_u32 s32, 0x4000
	s_cbranch_scc1 .Lnorm_full
	global_load_dwordx4 v[30:33], v[2:3], off
	global_load_dwordx4 v[26:29], v[2:3], off offset:1024
	global_load_dwordx4 v[22:25], v[2:3], off offset:2048
	global_load_dwordx4 v[18:21], v[2:3], off offset:3072
	v_add_co_u32_e32 v2, vcc, s16, v2
	s_nop 1
	v_addc_co_u32_e32 v3, vcc, 0, v3, vcc
	global_load_dwordx4 v[14:17], v[2:3], off
	global_load_dwordx4 v[6:9], v[2:3], off offset:1024
	global_load_dwordx4 v[82:85], v[2:3], off offset:2048
	global_load_dwordx4 v[86:89], v[2:3], off offset:3072
	v_lshlrev_b64 v[72:73], 12, v[72:73]
	s_add_i32 s35, s32, 0x100
	s_lshr_b32 s78, s32, 11
	s_lshl_b32 s78, s78, 8
	s_and_b32 s81, s32, 0xff
	s_or_b32 s78, s78, s81
	s_add_i32 s78, s78, 0x4000
	s_and_b32 s41, s32, 0x700
	s_cmp_eq_u32 s41, 0x700
	s_cselect_b32 s35, s78, s35
	s_cmp_ge_u32 s32, 0x4000
	s_cselect_b32 s35, 0x4800, s35
	v_mov_b32_e32 v34, s35
	v_mov_b32_e32 v35, 0
	v_cmp_lt_i32_e32 vcc, s12, v34
	s_or_b64 s[8:9], vcc, s[8:9]
	v_lshl_add_u64 v[48:49], v[48:49], 0, s[98:99]
	v_lshl_add_u64 v[92:93], v[46:47], 0, v[72:73]
	s_waitcnt vmcnt(0)
	v_mul_f32_e32 v4, v31, v31
	v_mul_f32_e32 v5, v27, v27
	v_fmac_f32_e32 v4, v30, v30
	v_fmac_f32_e32 v5, v26, v26
	v_fmac_f32_e32 v4, v32, v32
	v_fmac_f32_e32 v5, v28, v28
	v_fmac_f32_e32 v4, v33, v33
	v_fmac_f32_e32 v5, v29, v29
	v_add_f32_e32 v4, v4, v5
	v_mul_f32_e32 v5, v23, v23
	v_fmac_f32_e32 v5, v22, v22
	v_fmac_f32_e32 v5, v24, v24
	v_fmac_f32_e32 v5, v25, v25
	v_add_f32_e32 v4, v4, v5
	v_mul_f32_e32 v5, v19, v19
	v_fmac_f32_e32 v5, v18, v18
	v_fmac_f32_e32 v5, v20, v20
	v_fmac_f32_e32 v5, v21, v21
	v_mov_b32_e32 v10, v15
	v_mov_b32_e32 v11, v7
	v_add_f32_e32 v12, v4, v5
	v_mov_b32_e32 v4, v14
	v_mov_b32_e32 v5, v6
	v_pk_mul_f32 v[10:11], v[10:11], v[10:11]
	s_nop 0
	v_pk_fma_f32 v[4:5], v[4:5], v[4:5], v[10:11]
	v_mov_b32_e32 v10, v16
	v_mov_b32_e32 v11, v8
	v_pk_fma_f32 v[4:5], v[10:11], v[10:11], v[4:5]
	v_mov_b32_e32 v10, v17
	v_mov_b32_e32 v11, v9
	v_pk_fma_f32 v[4:5], v[10:11], v[10:11], v[4:5]
	s_nop 0
	v_add_f32_e32 v4, v12, v4
	v_add_f32_e32 v66, v4, v5
	v_mov_b32_e32 v74, v83
	v_mov_b32_e32 v75, v87
	v_mov_b32_e32 v70, v82
	v_mov_b32_e32 v71, v86
	v_pk_mul_f32 v[74:75], v[74:75], v[74:75]
	s_nop 0
	v_pk_fma_f32 v[70:71], v[70:71], v[70:71], v[74:75]
	v_mov_b32_e32 v74, v84
	v_mov_b32_e32 v75, v88
	v_pk_fma_f32 v[70:71], v[74:75], v[74:75], v[70:71]
	v_mov_b32_e32 v74, v85
	v_mov_b32_e32 v75, v89
	v_pk_fma_f32 v[70:71], v[74:75], v[74:75], v[70:71]
	s_nop 0
	v_add_f32_e32 v66, v66, v70
	v_add_f32_e32 v66, v66, v71
	ds_bpermute_b32 v70, v67, v66
	s_waitcnt lgkmcnt(0)
	v_add_f32_e32 v66, v66, v70
	ds_bpermute_b32 v70, v76, v66
	s_waitcnt lgkmcnt(0)
	v_add_f32_e32 v66, v66, v70
	ds_bpermute_b32 v70, v77, v66
	s_waitcnt lgkmcnt(0)
	v_add_f32_e32 v66, v66, v70
	ds_bpermute_b32 v70, v78, v66
	s_waitcnt lgkmcnt(0)
	v_add_f32_e32 v66, v66, v70
	ds_bpermute_b32 v70, v79, v66
	s_waitcnt lgkmcnt(0)
	v_add_f32_e32 v66, v66, v70
	ds_bpermute_b32 v70, v80, v66
	s_waitcnt lgkmcnt(0)
	v_add_f32_e32 v66, v66, v70
	v_fmamk_f32 v66, v66, 0x3a000000, v230
	v_cmp_gt_f32_e32 vcc, s70, v66
	v_mul_f32_e32 v70, 0x4b800000, v66
	s_nop 0
	v_cndmask_b32_e32 v66, v66, v70, vcc
	v_rsq_f32_e32 v66, v66
	s_nop 0
	v_mul_f32_e32 v70, 0x45800000, v66
	v_cndmask_b32_e32 v66, v66, v70, vcc
	v_pk_mul_f32 v[30:31], v[30:31], v[66:67] op_sel_hi:[1,0]
	v_pk_mul_f32 v[32:33], v[32:33], v[66:67] op_sel_hi:[1,0]
	v_pk_mul_f32 v[26:27], v[26:27], v[66:67] op_sel_hi:[1,0]
	v_pk_mul_f32 v[28:29], v[28:29], v[66:67] op_sel_hi:[1,0]
	v_pk_mul_f32 v[22:23], v[22:23], v[66:67] op_sel_hi:[1,0]
	v_pk_mul_f32 v[24:25], v[24:25], v[66:67] op_sel_hi:[1,0]
	v_pk_mul_f32 v[18:19], v[18:19], v[66:67] op_sel_hi:[1,0]
	v_pk_mul_f32 v[20:21], v[20:21], v[66:67] op_sel_hi:[1,0]
	v_pk_mul_f32 v[14:15], v[14:15], v[66:67] op_sel_hi:[1,0]
	v_pk_mul_f32 v[16:17], v[16:17], v[66:67] op_sel_hi:[1,0]
	v_pk_mul_f32 v[6:7], v[6:7], v[66:67] op_sel_hi:[1,0]
	v_pk_mul_f32 v[8:9], v[8:9], v[66:67] op_sel_hi:[1,0]
	v_pk_mul_f32 v[82:83], v[82:83], v[66:67] op_sel_hi:[1,0]
	v_pk_mul_f32 v[84:85], v[84:85], v[66:67] op_sel_hi:[1,0]
	v_pk_mul_f32 v[86:87], v[86:87], v[66:67] op_sel_hi:[1,0]
	v_pk_mul_f32 v[88:89], v[88:89], v[66:67] op_sel_hi:[1,0]
	v_pk_mul_f32 v[30:31], v[94:95], v[30:31]
	v_pk_mul_f32 v[32:33], v[96:97], v[32:33]
	v_pk_add_f32 v[4:5], v[158:159], 1.0 op_sel_hi:[1,0]
	v_pk_add_f32 v[10:11], v[160:161], 1.0 op_sel_hi:[1,0]
	v_pk_fma_f32 v[30:31], v[4:5], v[30:31], v[126:127]
	v_pk_fma_f32 v[32:33], v[10:11], v[32:33], v[128:129]
	v_cvt_pk_bf16_f32 v12, v30, v31
	v_cvt_pk_bf16_f32 v13, v32, v33
	global_store_dwordx2 v[92:93], v[12:13], off
	v_pk_mul_f32 v[26:27], v[98:99], v[26:27]
	v_pk_mul_f32 v[28:29], v[100:101], v[28:29]
	v_pk_add_f32 v[4:5], v[162:163], 1.0 op_sel_hi:[1,0]
	v_pk_add_f32 v[10:11], v[164:165], 1.0 op_sel_hi:[1,0]
	v_pk_fma_f32 v[26:27], v[4:5], v[26:27], v[130:131]
	v_pk_fma_f32 v[28:29], v[10:11], v[28:29], v[132:133]
	v_cvt_pk_bf16_f32 v12, v26, v27
	v_cvt_pk_bf16_f32 v13, v28, v29
	global_store_dwordx2 v[92:93], v[12:13], off offset:512
	v_pk_mul_f32 v[22:23], v[102:103], v[22:23]
	v_pk_mul_f32 v[24:25], v[104:105], v[24:25]
	v_pk_add_f32 v[4:5], v[166:167], 1.0 op_sel_hi:[1,0]
	v_pk_add_f32 v[10:11], v[168:169], 1.0 op_sel_hi:[1,0]
	v_pk_fma_f32 v[22:23], v[4:5], v[22:23], v[134:135]
	v_pk_fma_f32 v[24:25], v[10:11], v[24:25], v[136:137]
	v_cvt_pk_bf16_f32 v12, v22, v23
	v_cvt_pk_bf16_f32 v13, v24, v25
	global_store_dwordx2 v[92:93], v[12:13], off offset:1024
	v_pk_mul_f32 v[18:19], v[106:107], v[18:19]
	v_pk_mul_f32 v[20:21], v[108:109], v[20:21]
	v_pk_add_f32 v[4:5], v[170:171], 1.0 op_sel_hi:[1,0]
	v_pk_add_f32 v[10:11], v[172:173], 1.0 op_sel_hi:[1,0]
	v_pk_fma_f32 v[18:19], v[4:5], v[18:19], v[138:139]
	v_pk_fma_f32 v[20:21], v[10:11], v[20:21], v[140:141]
	v_cvt_pk_bf16_f32 v12, v18, v19
	v_cvt_pk_bf16_f32 v13, v20, v21
	global_store_dwordx2 v[92:93], v[12:13], off offset:1536
	v_pk_mul_f32 v[14:15], v[110:111], v[14:15]
	v_pk_mul_f32 v[16:17], v[112:113], v[16:17]
	v_pk_add_f32 v[4:5], v[174:175], 1.0 op_sel_hi:[1,0]
	v_pk_add_f32 v[10:11], v[176:177], 1.0 op_sel_hi:[1,0]
	v_pk_fma_f32 v[14:15], v[4:5], v[14:15], v[142:143]
	v_pk_fma_f32 v[16:17], v[10:11], v[16:17], v[144:145]
	v_cvt_pk_bf16_f32 v12, v14, v15
	v_cvt_pk_bf16_f32 v13, v16, v17
	global_store_dwordx2 v[92:93], v[12:13], off offset:2048
	v_pk_mul_f32 v[6:7], v[114:115], v[6:7]
	v_pk_mul_f32 v[8:9], v[116:117], v[8:9]
	v_pk_add_f32 v[4:5], v[178:179], 1.0 op_sel_hi:[1,0]
	v_pk_add_f32 v[10:11], v[180:181], 1.0 op_sel_hi:[1,0]
	v_pk_fma_f32 v[6:7], v[4:5], v[6:7], v[146:147]
	v_pk_fma_f32 v[8:9], v[10:11], v[8:9], v[148:149]
	v_cvt_pk_bf16_f32 v12, v6, v7
	v_cvt_pk_bf16_f32 v13, v8, v9
	global_store_dwordx2 v[92:93], v[12:13], off offset:2560
	v_pk_mul_f32 v[82:83], v[118:119], v[82:83]
	v_pk_mul_f32 v[84:85], v[120:121], v[84:85]
	v_pk_add_f32 v[4:5], v[182:183], 1.0 op_sel_hi:[1,0]
	v_pk_add_f32 v[10:11], v[184:185], 1.0 op_sel_hi:[1,0]
	v_pk_fma_f32 v[82:83], v[4:5], v[82:83], v[150:151]
	v_pk_fma_f32 v[84:85], v[10:11], v[84:85], v[152:153]
	v_cvt_pk_bf16_f32 v12, v82, v83
	v_cvt_pk_bf16_f32 v13, v84, v85
	global_store_dwordx2 v[92:93], v[12:13], off offset:3072
	v_pk_mul_f32 v[86:87], v[122:123], v[86:87]
	v_pk_mul_f32 v[88:89], v[124:125], v[88:89]
	v_pk_add_f32 v[4:5], v[186:187], 1.0 op_sel_hi:[1,0]
	v_pk_add_f32 v[10:11], v[188:189], 1.0 op_sel_hi:[1,0]
	v_pk_fma_f32 v[86:87], v[4:5], v[86:87], v[154:155]
	v_pk_fma_f32 v[88:89], v[10:11], v[88:89], v[156:157]
	v_cvt_pk_bf16_f32 v12, v86, v87
	v_cvt_pk_bf16_f32 v13, v88, v89
	global_store_dwordx2 v[92:93], v[12:13], off offset:3584
	s_branch .Lnorm_join
.Lnorm_full:
	global_load_dwordx4 v[30:33], v[2:3], off
	global_load_dwordx4 v[26:29], v[2:3], off offset:1024
	global_load_dwordx4 v[22:25], v[2:3], off offset:2048
	global_load_dwordx4 v[18:21], v[2:3], off offset:3072
	v_add_co_u32_e32 v2, vcc, s16, v2
	s_nop 1
	v_addc_co_u32_e32 v3, vcc, 0, v3, vcc
	global_load_dwordx4 v[14:17], v[2:3], off
	global_load_dwordx4 v[6:9], v[2:3], off offset:1024
	global_load_dwordx4 v[82:85], v[2:3], off offset:2048
	global_load_dwordx4 v[86:89], v[2:3], off offset:3072
	v_min_i32_e32 v81, 0x4000, v72
	v_ashrrev_i32_e32 v81, 11, v81
	v_mul_i32_i24_e32 v68, 0x1800, v81
	v_ashrrev_i32_e32 v69, 31, v68
	v_lshl_add_u64 v[68:69], v[68:69], 2, s[6:7]
	v_lshlrev_b64 v[72:73], 12, v[72:73]
	s_add_i32 s35, s32, 0x100
	s_lshr_b32 s78, s32, 11
	s_lshl_b32 s78, s78, 8
	s_and_b32 s81, s32, 0xff
	s_or_b32 s78, s78, s81
	s_add_i32 s78, s78, 0x4000
	s_and_b32 s41, s32, 0x700
	s_cmp_eq_u32 s41, 0x700
	s_cselect_b32 s35, s78, s35
	s_cmp_ge_u32 s32, 0x4000
	s_cselect_b32 s35, 0x4800, s35
	v_mov_b32_e32 v34, s35
	v_mov_b32_e32 v35, 0
	v_cmp_lt_i32_e32 vcc, s12, v34
	s_or_b64 s[8:9], vcc, s[8:9]
	v_lshl_add_u64 v[48:49], v[48:49], 0, s[98:99]
	v_lshl_add_u64 v[74:75], v[68:69], 0, v[50:51]
	v_lshl_add_u64 v[70:71], v[68:69], 0, s[22:23]
	v_lshl_add_u64 v[90:91], v[70:71], 0, v[50:51]
	v_lshl_add_u64 v[4:5], v[68:69], 0, v[58:59]
	v_lshl_add_u64 v[10:11], v[70:71], 0, v[58:59]
	v_lshl_add_u64 v[92:93], v[46:47], 0, v[72:73]
	global_load_dwordx4 v[94:97], v[36:37], off
	global_load_dwordx4 v[126:129], v[74:75], off
	global_load_dwordx4 v[158:161], v[90:91], off
	global_load_dwordx4 v[98:101], v[36:37], off offset:1024
	global_load_dwordx4 v[130:133], v[74:75], off offset:1024
	global_load_dwordx4 v[162:165], v[90:91], off offset:1024
	global_load_dwordx4 v[102:105], v[36:37], off offset:2048
	global_load_dwordx4 v[134:137], v[74:75], off offset:2048
	global_load_dwordx4 v[166:169], v[90:91], off offset:2048
	global_load_dwordx4 v[106:109], v[36:37], off offset:3072
	global_load_dwordx4 v[138:141], v[74:75], off offset:3072
	global_load_dwordx4 v[170:173], v[90:91], off offset:3072
	global_load_dwordx4 v[110:113], v[38:39], off
	global_load_dwordx4 v[142:145], v[4:5], off
	global_load_dwordx4 v[174:177], v[10:11], off
	global_load_dwordx4 v[114:117], v[38:39], off offset:1024
	global_load_dwordx4 v[146:149], v[4:5], off offset:1024
	global_load_dwordx4 v[178:181], v[10:11], off offset:1024
	global_load_dwordx4 v[118:121], v[38:39], off offset:2048
	global_load_dwordx4 v[150:153], v[4:5], off offset:2048
	global_load_dwordx4 v[182:185], v[10:11], off offset:2048
	global_load_dwordx4 v[122:125], v[38:39], off offset:3072
	global_load_dwordx4 v[154:157], v[4:5], off offset:3072
	global_load_dwordx4 v[186:189], v[10:11], off offset:3072
	s_waitcnt vmcnt(24)
	v_mul_f32_e32 v4, v31, v31
	v_mul_f32_e32 v5, v27, v27
	v_fmac_f32_e32 v4, v30, v30
	v_fmac_f32_e32 v5, v26, v26
	v_fmac_f32_e32 v4, v32, v32
	v_fmac_f32_e32 v5, v28, v28
	v_fmac_f32_e32 v4, v33, v33
	v_fmac_f32_e32 v5, v29, v29
	v_add_f32_e32 v4, v4, v5
	v_mul_f32_e32 v5, v23, v23
	v_fmac_f32_e32 v5, v22, v22
	v_fmac_f32_e32 v5, v24, v24
	v_fmac_f32_e32 v5, v25, v25
	v_add_f32_e32 v4, v4, v5
	v_mul_f32_e32 v5, v19, v19
	v_fmac_f32_e32 v5, v18, v18
	v_fmac_f32_e32 v5, v20, v20
	v_fmac_f32_e32 v5, v21, v21
	v_mov_b32_e32 v10, v15
	v_mov_b32_e32 v11, v7
	v_add_f32_e32 v12, v4, v5
	v_mov_b32_e32 v4, v14
	v_mov_b32_e32 v5, v6
	v_pk_mul_f32 v[10:11], v[10:11], v[10:11]
	s_nop 0
	v_pk_fma_f32 v[4:5], v[4:5], v[4:5], v[10:11]
	v_mov_b32_e32 v10, v16
	v_mov_b32_e32 v11, v8
	v_pk_fma_f32 v[4:5], v[10:11], v[10:11], v[4:5]
	v_mov_b32_e32 v10, v17
	v_mov_b32_e32 v11, v9
	v_pk_fma_f32 v[4:5], v[10:11], v[10:11], v[4:5]
	s_nop 0
	v_add_f32_e32 v4, v12, v4
	v_add_f32_e32 v66, v4, v5
	v_mov_b32_e32 v74, v83
	v_mov_b32_e32 v75, v87
	v_mov_b32_e32 v70, v82
	v_mov_b32_e32 v71, v86
	v_pk_mul_f32 v[74:75], v[74:75], v[74:75]
	s_nop 0
	v_pk_fma_f32 v[70:71], v[70:71], v[70:71], v[74:75]
	v_mov_b32_e32 v74, v84
	v_mov_b32_e32 v75, v88
	v_pk_fma_f32 v[70:71], v[74:75], v[74:75], v[70:71]
	v_mov_b32_e32 v74, v85
	v_mov_b32_e32 v75, v89
	v_pk_fma_f32 v[70:71], v[74:75], v[74:75], v[70:71]
	s_nop 0
	v_add_f32_e32 v66, v66, v70
	v_add_f32_e32 v66, v66, v71
	ds_bpermute_b32 v70, v67, v66
	s_waitcnt lgkmcnt(0)
	v_add_f32_e32 v66, v66, v70
	ds_bpermute_b32 v70, v76, v66
	s_waitcnt lgkmcnt(0)
	v_add_f32_e32 v66, v66, v70
	ds_bpermute_b32 v70, v77, v66
	s_waitcnt lgkmcnt(0)
	v_add_f32_e32 v66, v66, v70
	ds_bpermute_b32 v70, v78, v66
	s_waitcnt lgkmcnt(0)
	v_add_f32_e32 v66, v66, v70
	ds_bpermute_b32 v70, v79, v66
	s_waitcnt lgkmcnt(0)
	v_add_f32_e32 v66, v66, v70
	ds_bpermute_b32 v70, v80, v66
	s_waitcnt lgkmcnt(0)
	v_add_f32_e32 v66, v66, v70
	v_fmamk_f32 v66, v66, 0x3a000000, v230
	v_cmp_gt_f32_e32 vcc, s70, v66
	v_mul_f32_e32 v70, 0x4b800000, v66
	s_nop 0
	v_cndmask_b32_e32 v66, v66, v70, vcc
	v_rsq_f32_e32 v66, v66
	s_nop 0
	v_mul_f32_e32 v70, 0x45800000, v66
	v_cndmask_b32_e32 v66, v66, v70, vcc
	v_pk_mul_f32 v[30:31], v[30:31], v[66:67] op_sel_hi:[1,0]
	v_pk_mul_f32 v[32:33], v[32:33], v[66:67] op_sel_hi:[1,0]
	v_pk_mul_f32 v[26:27], v[26:27], v[66:67] op_sel_hi:[1,0]
	v_pk_mul_f32 v[28:29], v[28:29], v[66:67] op_sel_hi:[1,0]
	v_pk_mul_f32 v[22:23], v[22:23], v[66:67] op_sel_hi:[1,0]
	v_pk_mul_f32 v[24:25], v[24:25], v[66:67] op_sel_hi:[1,0]
	v_pk_mul_f32 v[18:19], v[18:19], v[66:67] op_sel_hi:[1,0]
	v_pk_mul_f32 v[20:21], v[20:21], v[66:67] op_sel_hi:[1,0]
	v_pk_mul_f32 v[14:15], v[14:15], v[66:67] op_sel_hi:[1,0]
	v_pk_mul_f32 v[16:17], v[16:17], v[66:67] op_sel_hi:[1,0]
	v_pk_mul_f32 v[6:7], v[6:7], v[66:67] op_sel_hi:[1,0]
	v_pk_mul_f32 v[8:9], v[8:9], v[66:67] op_sel_hi:[1,0]
	v_pk_mul_f32 v[82:83], v[82:83], v[66:67] op_sel_hi:[1,0]
	v_pk_mul_f32 v[84:85], v[84:85], v[66:67] op_sel_hi:[1,0]
	v_pk_mul_f32 v[86:87], v[86:87], v[66:67] op_sel_hi:[1,0]
	v_pk_mul_f32 v[88:89], v[88:89], v[66:67] op_sel_hi:[1,0]
	s_waitcnt vmcnt(21)
	v_pk_mul_f32 v[30:31], v[94:95], v[30:31]
	v_pk_mul_f32 v[32:33], v[96:97], v[32:33]
	v_pk_add_f32 v[4:5], v[158:159], 1.0 op_sel_hi:[1,0]
	v_pk_add_f32 v[10:11], v[160:161], 1.0 op_sel_hi:[1,0]
	v_pk_fma_f32 v[30:31], v[4:5], v[30:31], v[126:127]
	v_pk_fma_f32 v[32:33], v[10:11], v[32:33], v[128:129]
	v_cvt_pk_bf16_f32 v12, v30, v31
	v_cvt_pk_bf16_f32 v13, v32, v33
	global_store_dwordx2 v[92:93], v[12:13], off
	s_waitcnt vmcnt(19)
	v_pk_mul_f32 v[26:27], v[98:99], v[26:27]
	v_pk_mul_f32 v[28:29], v[100:101], v[28:29]
	v_pk_add_f32 v[4:5], v[162:163], 1.0 op_sel_hi:[1,0]
	v_pk_add_f32 v[10:11], v[164:165], 1.0 op_sel_hi:[1,0]
	v_pk_fma_f32 v[26:27], v[4:5], v[26:27], v[130:131]
	v_pk_fma_f32 v[28:29], v[10:11], v[28:29], v[132:133]
	v_cvt_pk_bf16_f32 v12, v26, v27
	v_cvt_pk_bf16_f32 v13, v28, v29
	global_store_dwordx2 v[92:93], v[12:13], off offset:512
	s_waitcnt vmcnt(17)
	v_pk_mul_f32 v[22:23], v[102:103], v[22:23]
	v_pk_mul_f32 v[24:25], v[104:105], v[24:25]
	v_pk_add_f32 v[4:5], v[166:167], 1.0 op_sel_hi:[1,0]
	v_pk_add_f32 v[10:11], v[168:169], 1.0 op_sel_hi:[1,0]
	v_pk_fma_f32 v[22:23], v[4:5], v[22:23], v[134:135]
	v_pk_fma_f32 v[24:25], v[10:11], v[24:25], v[136:137]
	v_cvt_pk_bf16_f32 v12, v22, v23
	v_cvt_pk_bf16_f32 v13, v24, v25
	global_store_dwordx2 v[92:93], v[12:13], off offset:1024
	s_waitcnt vmcnt(15)
	v_pk_mul_f32 v[18:19], v[106:107], v[18:19]
	v_pk_mul_f32 v[20:21], v[108:109], v[20:21]
	v_pk_add_f32 v[4:5], v[170:171], 1.0 op_sel_hi:[1,0]
	v_pk_add_f32 v[10:11], v[172:173], 1.0 op_sel_hi:[1,0]
	v_pk_fma_f32 v[18:19], v[4:5], v[18:19], v[138:139]
	v_pk_fma_f32 v[20:21], v[10:11], v[20:21], v[140:141]
	v_cvt_pk_bf16_f32 v12, v18, v19
	v_cvt_pk_bf16_f32 v13, v20, v21
	global_store_dwordx2 v[92:93], v[12:13], off offset:1536
	s_waitcnt vmcnt(13)
	v_pk_mul_f32 v[14:15], v[110:111], v[14:15]
	v_pk_mul_f32 v[16:17], v[112:113], v[16:17]
	v_pk_add_f32 v[4:5], v[174:175], 1.0 op_sel_hi:[1,0]
	v_pk_add_f32 v[10:11], v[176:177], 1.0 op_sel_hi:[1,0]
	v_pk_fma_f32 v[14:15], v[4:5], v[14:15], v[142:143]
	v_pk_fma_f32 v[16:17], v[10:11], v[16:17], v[144:145]
	v_cvt_pk_bf16_f32 v12, v14, v15
	v_cvt_pk_bf16_f32 v13, v16, v17
	global_store_dwordx2 v[92:93], v[12:13], off offset:2048
	s_waitcnt vmcnt(11)
	v_pk_mul_f32 v[6:7], v[114:115], v[6:7]
	v_pk_mul_f32 v[8:9], v[116:117], v[8:9]
	v_pk_add_f32 v[4:5], v[178:179], 1.0 op_sel_hi:[1,0]
	v_pk_add_f32 v[10:11], v[180:181], 1.0 op_sel_hi:[1,0]
	v_pk_fma_f32 v[6:7], v[4:5], v[6:7], v[146:147]
	v_pk_fma_f32 v[8:9], v[10:11], v[8:9], v[148:149]
	v_cvt_pk_bf16_f32 v12, v6, v7
	v_cvt_pk_bf16_f32 v13, v8, v9
	global_store_dwordx2 v[92:93], v[12:13], off offset:2560
	s_waitcnt vmcnt(9)
	v_pk_mul_f32 v[82:83], v[118:119], v[82:83]
	v_pk_mul_f32 v[84:85], v[120:121], v[84:85]
	v_pk_add_f32 v[4:5], v[182:183], 1.0 op_sel_hi:[1,0]
	v_pk_add_f32 v[10:11], v[184:185], 1.0 op_sel_hi:[1,0]
	v_pk_fma_f32 v[82:83], v[4:5], v[82:83], v[150:151]
	v_pk_fma_f32 v[84:85], v[10:11], v[84:85], v[152:153]
	v_cvt_pk_bf16_f32 v12, v82, v83
	v_cvt_pk_bf16_f32 v13, v84, v85
	global_store_dwordx2 v[92:93], v[12:13], off offset:3072
	s_waitcnt vmcnt(7)
	v_pk_mul_f32 v[86:87], v[122:123], v[86:87]
	v_pk_mul_f32 v[88:89], v[124:125], v[88:89]
	v_pk_add_f32 v[4:5], v[186:187], 1.0 op_sel_hi:[1,0]
	v_pk_add_f32 v[10:11], v[188:189], 1.0 op_sel_hi:[1,0]
	v_pk_fma_f32 v[86:87], v[4:5], v[86:87], v[154:155]
	v_pk_fma_f32 v[88:89], v[10:11], v[88:89], v[156:157]
	v_cvt_pk_bf16_f32 v12, v86, v87
	v_cvt_pk_bf16_f32 v13, v88, v89
	global_store_dwordx2 v[92:93], v[12:13], off offset:3584
.Lnorm_join:
	s_andn2_b64 exec, exec, s[8:9]
	s_cbranch_execz .LBB0_86
